# FoX forget-bias LDS reads issued before the last QK MFMAs (after the last K fragment wait) instead of at the start of the softmax part
# baseline (speedup 1.0000x reference)
; #define MFMA(a, b, c) __builtin_amdgcn_mfma_f32_16x16x32_bf16((a), (b), (c), 0, 0, 0)
; template <int DK, bool BIAS> ...
;     ...
;       for (int ks = 0; ks < KS; ++ks)
; #pragma unroll
;         for (int kt = 0; kt < 4; ++kt) { const bf16x8 ak = *(const bf16x8*)(Ksm + (buf * 64 + 16 * kt + fr) * KST + 32 * ks + 8 * fq);
; #pragma unroll
;           for (int qi = 0; qi < 2; ++qi) S[kt][qi] = MFMA(ak, qf[qi][ks], S[kt][qi]); }
;       bf16x8 pf[2][2];
;       if (64 * j + 63 > q0 + 32 * w) {
; #pragma unroll
;         for (int qi = 0; qi < 2; ++qi) { const int qg = q0 + 32 * w + 16 * qi + fr;
; #pragma unroll
;           for (int kt = 0; kt < 4; ++kt)
; #pragma unroll
;             for (int r = 0; r < 4; ++r) { const int kg = 64 * j + 16 * kt + 4 * fq + r; if (kg > qg) S[kt][qi][r] = -1e30f; } }
;       }
.LBB0_1772:
	s_and_saveexec_b64 s[0:1], s[8:9]
	s_cbranch_execz .LBB0_1778
	v_cmp_le_i32_e32 vcc, s38, v167
	s_and_saveexec_b64 s[94:95], vcc
	s_cbranch_execz .LBB0_1777
	ds_read_b128 v[80:83], v169 offset:4608
	ds_read_b128 v[64:67], v169
	ds_read_b128 v[84:87], v169 offset:64
	ds_read_b128 v[72:75], v169 offset:2304
	ds_read_b128 v[210:213], v169 offset:6912
	ds_read_b128 v[214:217], v169 offset:2368
	ds_read_b128 v[218:221], v169 offset:6976
	ds_read_b128 v[222:225], v169 offset:4672
	s_add_i32 s18, s38, 63
	v_cmp_gt_i32_e32 vcc, s18, v127
	s_waitcnt lgkmcnt(7)
	v_mfma_f32_16x16x32_bf16 v[90:93], v[80:83], v[4:7], 0
	v_mfma_f32_16x16x32_bf16 v[94:97], v[80:83], v[12:15], 0
	s_waitcnt lgkmcnt(6)
	v_mfma_f32_16x16x32_bf16 v[68:71], v[64:67], v[4:7], 0
	s_waitcnt lgkmcnt(3)
	v_mfma_f32_16x16x32_bf16 v[116:119], v[210:213], v[4:7], 0
	v_mfma_f32_16x16x32_bf16 v[120:123], v[210:213], v[12:15], 0
	v_mfma_f32_16x16x32_bf16 v[80:83], v[84:87], v[0:3], v[68:71]
	v_mfma_f32_16x16x32_bf16 v[64:67], v[64:67], v[12:15], 0
	v_mfma_f32_16x16x32_bf16 v[76:79], v[72:75], v[4:7], 0
	v_mfma_f32_16x16x32_bf16 v[72:75], v[72:75], v[12:15], 0
	v_mfma_f32_16x16x32_bf16 v[64:67], v[84:87], v[8:11], v[64:67]
	s_waitcnt lgkmcnt(2)
	v_mfma_f32_16x16x32_bf16 v[86:89], v[214:217], v[0:3], v[76:79]
	v_mfma_f32_16x16x32_bf16 v[68:71], v[214:217], v[8:11], v[72:75]
	s_waitcnt lgkmcnt(0)
	ds_read_b128 v[174:177], v168 offset:36864
	ds_read_b128 v[194:197], v168 offset:36928
	ds_read_b128 v[242:245], v168 offset:36992
	ds_read_b128 v[246:249], v168 offset:37056
	v_mfma_f32_16x16x32_bf16 v[90:93], v[222:225], v[0:3], v[90:93]
	v_mfma_f32_16x16x32_bf16 v[72:75], v[222:225], v[8:11], v[94:97]
	v_mfma_f32_16x16x32_bf16 v[94:97], v[218:221], v[0:3], v[116:119]
	v_mfma_f32_16x16x32_bf16 v[76:79], v[218:221], v[8:11], v[120:123]
	s_and_saveexec_b64 s[18:19], vcc
	s_cbranch_execz .LBB0_1776
	v_add_u32_e32 v85, s38, v103
	v_mov_b32_e32 v84, s30
	v_cmp_gt_i32_e32 vcc, v85, v158
	v_add_u32_e32 v113, 2, v85
	v_add_u32_e32 v115, 3, v85
	v_cndmask_b32_e32 v84, v80, v84, vcc
	v_cmp_lt_i32_e32 vcc, v85, v158
	v_add_u32_e32 v116, 16, v85
	v_add_u32_e32 v117, 17, v85
	v_cndmask_b32_e32 v80, v84, v80, vcc
	v_cndmask_b32_e32 v81, v193, v81, vcc
	v_cmp_le_i32_e32 vcc, v113, v158
	v_mov_b32_e32 v84, s30
	v_add_u32_e32 v118, 18, v85
	v_cndmask_b32_e32 v82, v193, v82, vcc
	v_cmp_le_i32_e32 vcc, v115, v158
	v_add_u32_e32 v119, 19, v85
	v_add_u32_e32 v120, 32, v85
	v_cndmask_b32_e32 v83, v193, v83, vcc
	v_cmp_gt_i32_e32 vcc, v116, v158
	v_add_u32_e32 v121, 33, v85
	v_add_u32_e32 v122, 34, v85
	v_cndmask_b32_e32 v86, v86, v84, vcc
	v_cmp_le_i32_e32 vcc, v117, v158
	v_add_u32_e32 v123, 35, v85
	v_add_u32_e32 v124, 48, v85
	v_cndmask_b32_e32 v87, v193, v87, vcc
	v_cmp_le_i32_e32 vcc, v118, v158
	v_add_u32_e32 v125, 49, v85
	v_add_u32_e32 v126, 50, v85
	v_cndmask_b32_e32 v88, v193, v88, vcc
	v_cmp_le_i32_e32 vcc, v119, v158
	v_add_u32_e32 v131, 51, v85
	s_nop 0
	v_cndmask_b32_e32 v89, v193, v89, vcc
	v_cmp_gt_i32_e32 vcc, v120, v158
	v_cmp_le_i32_e64 s[100:101], v121, v158
	s_nop 0
	v_cndmask_b32_e32 v90, v90, v84, vcc
	v_cndmask_b32_e64 v91, v193, v91, s[100:101]
	v_cmp_le_i32_e32 vcc, v122, v158
	v_cmp_le_i32_e64 s[100:101], v123, v158
	s_nop 0
	v_cndmask_b32_e32 v92, v193, v92, vcc
	v_cndmask_b32_e64 v93, v193, v93, s[100:101]
	v_cmp_gt_i32_e32 vcc, v124, v158
	v_cmp_le_i32_e64 s[100:101], v125, v158
	s_nop 0
	v_cndmask_b32_e32 v94, v94, v84, vcc
	v_cndmask_b32_e64 v95, v193, v95, s[100:101]
	v_cmp_le_i32_e32 vcc, v126, v158
	v_cmp_le_i32_e64 s[100:101], v131, v158
	s_nop 0
	v_cndmask_b32_e32 v96, v193, v96, vcc
	v_cndmask_b32_e64 v97, v193, v97, s[100:101]
	v_cmp_gt_i32_e32 vcc, v85, v105
	s_nop 1
	v_cndmask_b32_e32 v84, v64, v84, vcc
	v_cmp_lt_i32_e32 vcc, v85, v105
	s_nop 1
	v_cndmask_b32_e32 v64, v84, v64, vcc
	v_cndmask_b32_e32 v65, v193, v65, vcc
	v_cmp_le_i32_e32 vcc, v113, v105
	v_mov_b32_e32 v84, s30
	s_nop 0
	v_cndmask_b32_e32 v66, v193, v66, vcc
	v_cmp_le_i32_e32 vcc, v115, v105
	v_cmp_gt_i32_e64 s[100:101], v116, v105
	s_nop 0
	v_cndmask_b32_e32 v67, v193, v67, vcc
	v_cndmask_b32_e64 v68, v68, v84, s[100:101]
	v_cmp_le_i32_e32 vcc, v117, v105
	v_cmp_le_i32_e64 s[100:101], v118, v105
	s_nop 0
	v_cndmask_b32_e32 v69, v193, v69, vcc
	v_cndmask_b32_e64 v70, v193, v70, s[100:101]
	v_cmp_le_i32_e32 vcc, v119, v105
	v_cmp_gt_i32_e64 s[100:101], v120, v105
	s_nop 0
	v_cndmask_b32_e32 v71, v193, v71, vcc
	v_cndmask_b32_e64 v72, v72, v84, s[100:101]
	v_cmp_le_i32_e32 vcc, v121, v105
	v_cmp_le_i32_e64 s[100:101], v122, v105
	s_nop 0
	v_cndmask_b32_e32 v73, v193, v73, vcc
	v_cndmask_b32_e64 v74, v193, v74, s[100:101]
	v_cmp_le_i32_e32 vcc, v123, v105
	v_cmp_gt_i32_e64 s[100:101], v124, v105
	s_nop 0
	v_cndmask_b32_e32 v75, v193, v75, vcc
	v_cndmask_b32_e64 v76, v76, v84, s[100:101]
	v_cmp_le_i32_e32 vcc, v125, v105
	v_cmp_le_i32_e64 s[100:101], v126, v105
	s_nop 0
	v_cndmask_b32_e32 v77, v193, v77, vcc
	v_cndmask_b32_e64 v78, v193, v78, s[100:101]
	v_cmp_le_i32_e32 vcc, v131, v105
	s_nop 1
	v_cndmask_b32_e32 v79, v193, v79, vcc

; #define MFMA(a, b, c) __builtin_amdgcn_mfma_f32_16x16x32_bf16((a), (b), (c), 0, 0, 0)
; template <int DK, bool BIAS> ...
;     ...
;       for (int ks = 0; ks < KS; ++ks)
; #pragma unroll
;         for (int kt = 0; kt < 4; ++kt) { const bf16x8 ak = *(const bf16x8*)(Ksm + (buf * 64 + 16 * kt + fr) * KST + 32 * ks + 8 * fq);
; #pragma unroll
;           for (int qi = 0; qi < 2; ++qi) S[kt][qi] = MFMA(ak, qf[qi][ks], S[kt][qi]); }
;       bf16x8 pf[2][2];
;       if (64 * j + 63 > q0 + 32 * w) {
; #pragma unroll
;         for (int qi = 0; qi < 2; ++qi) { const int qg = q0 + 32 * w + 16 * qi + fr;
; #pragma unroll
;           for (int kt = 0; kt < 4; ++kt)
; #pragma unroll
;             for (int r = 0; r < 4; ++r) { const int kg = 64 * j + 16 * kt + 4 * fq + r; if (kg > qg) S[kt][qi][r] = -1e30f; } }
;       }
.LBB0_1793:
	s_and_saveexec_b64 s[0:1], s[8:9]
	s_cbranch_execz .LBB0_1799
	s_add_i32 s18, s38, 64
	v_cmp_le_i32_e32 vcc, s18, v167
	s_and_saveexec_b64 s[92:93], vcc
	s_cbranch_execz .LBB0_1798
	ds_read_b128 v[80:83], v169 offset:13824
	ds_read_b128 v[64:67], v169 offset:9216
	ds_read_b128 v[84:87], v169 offset:9280
	ds_read_b128 v[72:75], v169 offset:11520
	ds_read_b128 v[210:213], v169 offset:16128
	ds_read_b128 v[214:217], v169 offset:11584
	ds_read_b128 v[218:221], v169 offset:16192
	ds_read_b128 v[222:225], v169 offset:13888
	s_add_i32 s18, s38, 0x7f
	v_cmp_gt_i32_e32 vcc, s18, v127
	s_waitcnt lgkmcnt(7)
	v_mfma_f32_16x16x32_bf16 v[90:93], v[80:83], v[4:7], 0
	v_mfma_f32_16x16x32_bf16 v[94:97], v[80:83], v[12:15], 0
	s_waitcnt lgkmcnt(6)
	v_mfma_f32_16x16x32_bf16 v[68:71], v[64:67], v[4:7], 0
	s_waitcnt lgkmcnt(3)
	v_mfma_f32_16x16x32_bf16 v[116:119], v[210:213], v[4:7], 0
	v_mfma_f32_16x16x32_bf16 v[120:123], v[210:213], v[12:15], 0
	v_mfma_f32_16x16x32_bf16 v[80:83], v[84:87], v[0:3], v[68:71]
	v_mfma_f32_16x16x32_bf16 v[64:67], v[64:67], v[12:15], 0
	v_mfma_f32_16x16x32_bf16 v[76:79], v[72:75], v[4:7], 0
	v_mfma_f32_16x16x32_bf16 v[72:75], v[72:75], v[12:15], 0
	v_mfma_f32_16x16x32_bf16 v[64:67], v[84:87], v[8:11], v[64:67]
	s_waitcnt lgkmcnt(2)
	v_mfma_f32_16x16x32_bf16 v[86:89], v[214:217], v[0:3], v[76:79]
	v_mfma_f32_16x16x32_bf16 v[68:71], v[214:217], v[8:11], v[72:75]
	s_waitcnt lgkmcnt(0)
	ds_read_b128 v[174:177], v104 offset:37120
	ds_read_b128 v[194:197], v104 offset:37184
	ds_read_b128 v[242:245], v104 offset:37248
	ds_read_b128 v[246:249], v104 offset:37312
	v_mfma_f32_16x16x32_bf16 v[90:93], v[222:225], v[0:3], v[90:93]
	v_mfma_f32_16x16x32_bf16 v[72:75], v[222:225], v[8:11], v[94:97]
	v_mfma_f32_16x16x32_bf16 v[94:97], v[218:221], v[0:3], v[116:119]
	v_mfma_f32_16x16x32_bf16 v[76:79], v[218:221], v[8:11], v[120:123]
	s_and_saveexec_b64 s[18:19], vcc
	s_cbranch_execz .LBB0_1797
	v_add_u32_e32 v85, s38, v103
	v_add_u32_e32 v113, 64, v85
	v_mov_b32_e32 v84, s30
	v_cmp_gt_i32_e32 vcc, v113, v158
	v_add_u32_e32 v115, 0x42, v85
	v_add_u32_e32 v116, 0x43, v85
	v_cndmask_b32_e32 v84, v80, v84, vcc
	v_cmp_lt_i32_e32 vcc, v113, v158
	v_add_u32_e32 v117, 0x50, v85
	v_add_u32_e32 v118, 0x51, v85
	v_cndmask_b32_e32 v80, v84, v80, vcc
	v_cndmask_b32_e32 v81, v193, v81, vcc
	v_cmp_le_i32_e32 vcc, v115, v158
	v_mov_b32_e32 v84, s30
	v_add_u32_e32 v119, 0x52, v85
	v_cndmask_b32_e32 v82, v193, v82, vcc
	v_cmp_le_i32_e32 vcc, v116, v158
	v_add_u32_e32 v120, 0x53, v85
	v_add_u32_e32 v121, 0x60, v85
	v_cndmask_b32_e32 v83, v193, v83, vcc
	v_cmp_gt_i32_e32 vcc, v117, v158
	v_add_u32_e32 v122, 0x61, v85
	v_add_u32_e32 v123, 0x62, v85
	v_cndmask_b32_e32 v86, v86, v84, vcc
	v_cmp_le_i32_e32 vcc, v118, v158
	v_add_u32_e32 v124, 0x63, v85
	v_add_u32_e32 v125, 0x70, v85
	v_cndmask_b32_e32 v87, v193, v87, vcc
	v_cmp_le_i32_e32 vcc, v119, v158
	v_add_u32_e32 v126, 0x71, v85
	v_add_u32_e32 v131, 0x72, v85
	v_cndmask_b32_e32 v88, v193, v88, vcc
	v_cmp_le_i32_e32 vcc, v120, v158
	v_add_u32_e32 v85, 0x73, v85
	s_nop 0
	v_cndmask_b32_e32 v89, v193, v89, vcc
	v_cmp_gt_i32_e32 vcc, v121, v158
	v_cmp_le_i32_e64 s[100:101], v122, v158
	s_nop 0
	v_cndmask_b32_e32 v90, v90, v84, vcc
	v_cndmask_b32_e64 v91, v193, v91, s[100:101]
	v_cmp_le_i32_e32 vcc, v123, v158
	v_cmp_le_i32_e64 s[100:101], v124, v158
	s_nop 0
	v_cndmask_b32_e32 v92, v193, v92, vcc
	v_cndmask_b32_e64 v93, v193, v93, s[100:101]
	v_cmp_gt_i32_e32 vcc, v125, v158
	v_cmp_le_i32_e64 s[100:101], v126, v158
	s_nop 0
	v_cndmask_b32_e32 v94, v94, v84, vcc
	v_cndmask_b32_e64 v95, v193, v95, s[100:101]
	v_cmp_le_i32_e32 vcc, v131, v158
	v_cmp_le_i32_e64 s[100:101], v85, v158
	s_nop 0
	v_cndmask_b32_e32 v96, v193, v96, vcc
	v_cndmask_b32_e64 v97, v193, v97, s[100:101]
	v_cmp_gt_i32_e32 vcc, v113, v105
	s_nop 1
	v_cndmask_b32_e32 v84, v64, v84, vcc
	v_cmp_lt_i32_e32 vcc, v113, v105
	s_nop 1
	v_cndmask_b32_e32 v64, v84, v64, vcc
	v_cndmask_b32_e32 v65, v193, v65, vcc
	v_cmp_le_i32_e32 vcc, v115, v105
	v_mov_b32_e32 v84, s30
	s_nop 0
	v_cndmask_b32_e32 v66, v193, v66, vcc
	v_cmp_le_i32_e32 vcc, v116, v105
	v_cmp_gt_i32_e64 s[100:101], v117, v105
	s_nop 0
	v_cndmask_b32_e32 v67, v193, v67, vcc
	v_cndmask_b32_e64 v68, v68, v84, s[100:101]
	v_cmp_le_i32_e32 vcc, v118, v105
	v_cmp_le_i32_e64 s[100:101], v119, v105
	s_nop 0
	v_cndmask_b32_e32 v69, v193, v69, vcc
	v_cndmask_b32_e64 v70, v193, v70, s[100:101]
	v_cmp_le_i32_e32 vcc, v120, v105
	v_cmp_gt_i32_e64 s[100:101], v121, v105
	s_nop 0
	v_cndmask_b32_e32 v71, v193, v71, vcc
	v_cndmask_b32_e64 v72, v72, v84, s[100:101]
	v_cmp_le_i32_e32 vcc, v122, v105
	v_cmp_le_i32_e64 s[100:101], v123, v105
	s_nop 0
	v_cndmask_b32_e32 v73, v193, v73, vcc
	v_cndmask_b32_e64 v74, v193, v74, s[100:101]
	v_cmp_le_i32_e32 vcc, v124, v105
	v_cmp_gt_i32_e64 s[100:101], v125, v105
	s_nop 0
	v_cndmask_b32_e32 v75, v193, v75, vcc
	v_cndmask_b32_e64 v76, v76, v84, s[100:101]
	v_cmp_le_i32_e32 vcc, v126, v105
	v_cmp_le_i32_e64 s[100:101], v131, v105
	s_nop 0
	v_cndmask_b32_e32 v77, v193, v77, vcc
	v_cndmask_b32_e64 v78, v193, v78, s[100:101]
	v_cmp_le_i32_e32 vcc, v85, v105
	s_nop 1
	v_cndmask_b32_e32 v79, v193, v79, vcc
